# P2 attention: K/V/Q block loads (each byte read once) marked nt so the group outputs stay cache-resident for the merge pass
# baseline (speedup 1.0000x reference)
; __device__ __forceinline__ void attn_issue(AttnRegs& R, const AttnUnit& u, int blk, bool with_q, const bf16* qkv, const float* bias2) {
;     const int tid = threadIdx.x, lane = tid & 63, w = tid >> 6;
;     const int L = 4096 >> (2 * u.g), gh = u.g * 8 + u.h;
;     const int ch = tid & 15, r0 = tid >> 4;
;     if (with_q) R.tabv = bias2[gh * 192 + (tid < 192 ? tid : 0)];
;     const size_t rb = (size_t)(u.r * L + blk * 128 + r0) * 128 + ch * 8;
;     const bf16* kp = attn_plane(qkv, 1, u) + rb; const bf16* vp = attn_plane(qkv, 2, u) + rb;
; #pragma unroll
;     for (int j = 0; j < 4; ++j) { R.kr[j] = *(const v4u*)(kp + (size_t)j * 32 * 128); R.vr[j] = *(const v4u*)(vp + (size_t)j * 32 * 128); }
;     if (with_q) {
;         const int qi = 16 * w + (lane & 15), kg = lane >> 4;
;         const bf16* qp = attn_plane(qkv, 0, u) + (size_t)(u.r * L + u.n * 128 + qi) * 128 + 8 * kg;
; #pragma unroll
;         for (int s = 0; s < 4; ++s) R.qf[s] = *(const bf16x8*)(qp + 32 * s);
;     }
; }
.LBB0_145:
	s_add_u32 s0, s40, 0x3fc00000
	s_addc_u32 s1, s41, 0
	s_add_u32 s33, s40, 0xbc00000
	s_addc_u32 s46, s41, 0
	s_add_u32 s47, s38, 0x8000000
	s_addc_u32 s64, s39, 0
	s_add_i32 s4, s59, s10
	s_or_b32 s4, s4, s6
	s_ashr_i32 s5, s4, 31
	s_lshl_b64 s[4:5], s[4:5], 20
	v_lshrrev_b32_e32 v1, 2, v178
	s_add_u32 s4, s18, s4
	v_and_b32_e32 v33, 0xf0, v1
	s_addc_u32 s5, s19, s5
	v_or_b32_e32 v1, v33, v92
	s_add_i32 s8, s9, s8
	v_add_lshl_u32 v80, s8, v1, 8
	v_mov_b32_e32 v81, 0
	v_lshl_add_u64 v[2:3], s[4:5], 0, v[80:81]
	s_add_i32 s4, s58, s10
	v_lshrrev_b32_e32 v1, 1, v178
	s_ashr_i32 s5, s4, 31
	v_and_b32_e32 v34, 24, v1
	s_lshl_b64 s[4:5], s[4:5], 20
	v_lshlrev_b32_e32 v80, 1, v34
	v_add_u32_e32 v0, s9, v0
	s_add_u32 s4, s18, s4
	v_lshl_add_u64 v[2:3], v[2:3], 0, v[80:81]
	v_lshl_or_b32 v80, v0, 7, v91
	s_addc_u32 s5, s19, s5
	v_lshl_add_u64 v[12:13], v[80:81], 1, s[4:5]
	s_mov_b32 s65, 0x18006000
	v_add_co_u32_e32 v0, vcc, s65, v12
	s_mov_b32 s66, 0xc006000
	s_nop 0
	v_addc_co_u32_e32 v1, vcc, 0, v13, vcc
	global_load_dwordx4 v[48:51], v[2:3], off offset:192 nt
	global_load_dwordx4 v[52:55], v[2:3], off offset:128 nt
	global_load_dwordx4 v[56:59], v[2:3], off offset:64 nt
	global_load_dwordx4 v[60:63], v[2:3], off nt
	v_add_co_u32_e32 v2, vcc, s66, v12
	s_mov_b32 s67, 0x18004000
	s_nop 0
	v_addc_co_u32_e32 v3, vcc, 0, v13, vcc
	v_add_co_u32_e32 v4, vcc, s67, v12
	s_mov_b32 s68, 0xc004000
	s_nop 0
	v_addc_co_u32_e32 v5, vcc, 0, v13, vcc
	v_add_co_u32_e32 v6, vcc, s68, v12
	s_mov_b32 s69, 0x18002000
	s_nop 0
	v_addc_co_u32_e32 v7, vcc, 0, v13, vcc
	v_add_co_u32_e32 v8, vcc, s69, v12
	s_mov_b32 s70, 0xc002000
	s_nop 0
	v_addc_co_u32_e32 v9, vcc, 0, v13, vcc
	s_lshl_b32 s4, s7, 3
	v_add_co_u32_e32 v10, vcc, s70, v12
	s_or_b32 s4, s4, s6
	s_movk_i32 s5, 0xc0
	v_addc_co_u32_e32 v11, vcc, 0, v13, vcc
	s_brev_b32 s71, 24
	s_mul_i32 s6, s4, 0xc0
	v_cmp_gt_u32_e64 s[4:5], s5, v178
	v_add_co_u32_e32 v14, vcc, s71, v12
	s_nop 0
	v_cndmask_b32_e64 v95, 0, v178, s[4:5]
	v_addc_co_u32_e32 v15, vcc, 0, v13, vcc
	s_brev_b32 s72, 48
	v_add_u32_e32 v36, s6, v95
	v_add_co_u32_e32 v12, vcc, s72, v12
	v_ashrrev_i32_e32 v37, 31, v36
	s_nop 0
	v_addc_co_u32_e32 v13, vcc, 0, v13, vcc
	v_lshl_add_u64 v[36:37], v[36:37], 2, s[56:57]
	global_load_dwordx4 v[28:31], v[0:1], off nt
	s_nop 0
	global_load_dwordx4 v[0:3], v[2:3], off nt
	s_nop 0
	global_load_dwordx4 v[16:19], v[4:5], off nt
	s_nop 0
	global_load_dwordx4 v[4:7], v[6:7], off nt
	s_nop 0
	global_load_dwordx4 v[20:23], v[8:9], off nt
	s_nop 0
	global_load_dwordx4 v[8:11], v[10:11], off nt
	s_nop 0
	global_load_dwordx4 v[24:27], v[14:15], off nt
	s_nop 0
	global_load_dwordx4 v[12:15], v[12:13], off nt
	v_lshlrev_b32_e32 v35, 2, v178
	global_load_dword v125, v[36:37], off
	s_add_i32 s6, 0, 0x20000
	v_add_u32_e32 v97, s6, v35
	v_and_b32_e32 v102, 12, v35
	v_lshrrev_b32_e32 v35, 1, v92
	v_bfe_u32 v99, v178, 4, 2
	v_and_b32_e32 v35, 2, v35
	v_or_b32_e32 v98, v33, v92
	v_lshrrev_b32_e32 v33, 2, v92
	v_bitop3_b32 v36, v35, v99, v102 bitop3:0x36
	v_or_b32_e32 v104, 4, v99
	v_lshlrev_b32_e32 v100, 3, v33
	v_lshlrev_b32_e32 v103, 4, v36
	v_bitop3_b32 v36, v35, v104, v102 bitop3:0x36
	v_or_b32_e32 v106, 8, v99
	v_or_b32_e32 v108, 12, v99
	v_lshl_or_b32 v111, v99, 3, v33
	v_lshlrev_b32_e32 v33, 1, v90
	v_lshlrev_b32_e32 v105, 4, v36
	v_bitop3_b32 v36, v35, v106, v102 bitop3:0x36
	v_bitop3_b32 v35, v35, v108, v102 bitop3:0x36
	v_and_b32_e32 v113, 12, v178
	v_and_b32_e32 v33, 2, v33
	v_lshlrev_b32_e32 v109, 4, v35
	v_bfe_u32 v112, v178, 1, 1
	v_or_b32_e32 v35, v33, v113
	v_and_b32_e32 v114, 8, v32
	v_or_b32_e32 v32, v35, v112
	v_or_b32_e32 v116, 2, v112
	v_lshlrev_b32_e32 v115, 4, v32
	v_bitop3_b32 v32, v33, v116, v113 bitop3:0x36
	v_or_b32_e32 v118, 4, v112
	v_lshlrev_b32_e32 v117, 4, v32
	v_bitop3_b32 v32, v33, v118, v113 bitop3:0x36
	v_or_b32_e32 v120, 6, v112
	v_lshlrev_b32_e32 v119, 4, v32
	v_bitop3_b32 v32, v33, v120, v113 bitop3:0x36
	v_or_b32_e32 v122, 8, v112
	v_lshlrev_b32_e32 v121, 4, v32
	v_bitop3_b32 v32, v33, v122, v113 bitop3:0x36
	v_or_b32_e32 v124, 10, v112
	v_lshlrev_b32_e32 v123, 4, v32
	v_bitop3_b32 v32, v33, v124, v113 bitop3:0x36
	v_or_b32_e32 v127, 12, v112
	v_lshlrev_b32_e32 v126, 4, v32
	v_bitop3_b32 v32, v33, v127, v113 bitop3:0x36
	v_or_b32_e32 v129, 14, v112
	v_lshlrev_b32_e32 v128, 4, v32
	v_bitop3_b32 v32, v33, v129, v113 bitop3:0x36
	v_lshlrev_b32_e32 v130, 4, v32
	v_lshlrev_b32_e32 v32, 2, v99
	v_lshlrev_b32_e32 v84, 1, v32
	v_mbcnt_lo_u32_b32 v32, -1, 0
	s_mov_b32 s9, 0
	v_or_b32_e32 v96, 0x4000, v93
	v_and_b32_e32 v101, 3, v178
	v_lshlrev_b32_e32 v107, 4, v36
	v_lshl_add_u32 v110, v99, 5, s6
	v_cmp_eq_u32_e64 s[6:7], 0, v99
	s_add_i32 s73, 0, 0x10000
	v_lshlrev_b32_e32 v82, 1, v34
	s_mov_b32 s74, 0xf149f2ca
	v_mov_b32_e32 v131, 0xf149f2ca
	v_mbcnt_hi_u32_b32 v132, -1, v32
	s_waitcnt vmcnt(0)
	s_branch .LBB0_147

; __device__ __forceinline__ void attn_issue(AttnRegs& R, const AttnUnit& u, int blk, bool with_q, const bf16* qkv, const float* bias2) {
;     const int tid = threadIdx.x, lane = tid & 63, w = tid >> 6;
;     const int L = 4096 >> (2 * u.g), gh = u.g * 8 + u.h;
;     const int ch = tid & 15, r0 = tid >> 4;
;     if (with_q) R.tabv = bias2[gh * 192 + (tid < 192 ? tid : 0)];
;     const size_t rb = (size_t)(u.r * L + blk * 128 + r0) * 128 + ch * 8;
;     const bf16* kp = attn_plane(qkv, 1, u) + rb; const bf16* vp = attn_plane(qkv, 2, u) + rb;
; #pragma unroll
;     for (int j = 0; j < 4; ++j) { R.kr[j] = *(const v4u*)(kp + (size_t)j * 32 * 128); R.vr[j] = *(const v4u*)(vp + (size_t)j * 32 * 128); }
;     if (with_q) {
;         const int qi = 16 * w + (lane & 15), kg = lane >> 4;
;         const bf16* qp = attn_plane(qkv, 0, u) + (size_t)(u.r * L + u.n * 128 + qi) * 128 + 8 * kg;
; #pragma unroll
;         for (int s = 0; s < 4; ++s) R.qf[s] = *(const bf16x8*)(qp + 32 * s);
;     }
; }
; __global__ void __launch_bounds__(NTHREADS, 2) fwd_megakernel(Args args) {
;     ...
;             asm volatile("s_waitcnt lgkmcnt(0)" ::: "memory"); __builtin_amdgcn_s_barrier(); asm volatile("" ::: "memory");
;             if (uid + 1 < u1) { const AttnUnit un = attn_decode(uid + 1); attn_issue(R, un, un.n, true, PROJ, BIAS2); }
.LBB0_149:
	s_or_b64 exec, exec, s[58:59]
	s_add_i32 s75, s11, 1
	s_waitcnt lgkmcnt(0)
	s_barrier
	s_cmp_ge_i32 s75, s29
	s_cselect_b64 s[58:59], -1, 0
	v_mov_b64_e32 v[32:33], v[60:61]
	v_mov_b64_e32 v[36:37], v[56:57]
	v_mov_b64_e32 v[40:41], v[52:53]
	v_mov_b64_e32 v[44:45], v[48:49]
	s_and_b64 vcc, exec, s[58:59]
	v_mov_b64_e32 v[34:35], v[62:63]
	v_mov_b64_e32 v[38:39], v[58:59]
	v_mov_b64_e32 v[42:43], v[54:55]
	v_mov_b64_e32 v[46:47], v[50:51]
	s_cbranch_vccnz .LBB0_151
	s_ashr_i32 s31, s75, 8
	s_mul_hi_i32 s55, s31, 0x55555556
	s_lshr_b32 s60, s55, 31
	s_add_i32 s55, s55, s60
	s_mul_i32 s60, s55, 3
	s_sub_i32 s31, s31, s60
	s_lshl_b32 s60, s31, 1
	s_lshr_b32 s61, 32, s60
	s_and_b32 s30, s75, 31
	s_sub_i32 s76, 5, s60
	s_add_i32 s61, s61, -1
	s_bfe_u32 s54, s75, 0x30005
	s_lshr_b32 s76, s30, s76
	s_and_b32 s30, s61, s30
	s_lshl_b32 s61, s31, 3
	s_lshr_b32 s60, 0x1000, s60
	s_or_b32 s61, s61, s54
	s_mulk_i32 s61, 0xc0
	s_mul_i32 s76, s76, s60
	s_lshl_b32 s30, s30, 7
	s_lshl_b32 s55, s55, 3
	v_add_u32_e32 v0, s61, v95
	s_add_i32 s60, s30, s76
	s_lshl_b32 s61, s31, 6
	s_or_b32 s30, s55, s54
	s_add_i32 s30, s30, s61
	s_ashr_i32 s31, s30, 31
	s_lshl_b64 s[30:31], s[30:31], 20
	v_add_u32_e32 v2, s60, v90
	s_add_u32 s30, s18, s30
	v_lshl_or_b32 v80, v2, 7, v91
	s_addc_u32 s31, s19, s31
	v_lshl_add_u64 v[28:29], v[80:81], 1, s[30:31]
	v_ashrrev_i32_e32 v1, 31, v0
	v_add_co_u32_e32 v2, vcc, s72, v28
	v_lshl_add_u64 v[0:1], v[0:1], 2, s[56:57]
	s_nop 0
	v_addc_co_u32_e32 v3, vcc, 0, v29, vcc
	global_load_dword v125, v[0:1], off
	global_load_dwordx4 v[12:15], v[2:3], off nt
	v_add_co_u32_e32 v0, vcc, s71, v28
	s_add_i32 s55, s55, s61
	s_nop 0
	v_addc_co_u32_e32 v1, vcc, 0, v29, vcc
	v_add_co_u32_e32 v2, vcc, s70, v28
	s_or_b32 s30, s55, s54
	s_nop 0
	v_addc_co_u32_e32 v3, vcc, 0, v29, vcc
	global_load_dwordx4 v[24:27], v[0:1], off nt
	global_load_dwordx4 v[8:11], v[2:3], off nt
	v_add_co_u32_e32 v0, vcc, s69, v28
	s_ashr_i32 s31, s30, 31
	s_nop 0
	v_addc_co_u32_e32 v1, vcc, 0, v29, vcc
	v_add_co_u32_e32 v2, vcc, s68, v28
	s_lshl_b64 s[30:31], s[30:31], 20
	s_nop 0
	v_addc_co_u32_e32 v3, vcc, 0, v29, vcc
	global_load_dwordx4 v[20:23], v[0:1], off nt
	global_load_dwordx4 v[4:7], v[2:3], off nt
	v_add_co_u32_e32 v0, vcc, s67, v28
	s_add_u32 s30, s18, s30
	s_nop 0
	v_addc_co_u32_e32 v1, vcc, 0, v29, vcc
	v_add_co_u32_e32 v2, vcc, s66, v28
	s_addc_u32 s31, s19, s31
	s_nop 0
	v_addc_co_u32_e32 v3, vcc, 0, v29, vcc
	v_add_lshl_u32 v80, s60, v98, 8
	v_add_co_u32_e32 v28, vcc, s65, v28
	v_lshl_add_u64 v[30:31], s[30:31], 0, v[80:81]
	v_mov_b32_e32 v83, v81
	v_addc_co_u32_e32 v29, vcc, 0, v29, vcc
	v_lshl_add_u64 v[44:45], v[30:31], 0, v[82:83]
	global_load_dwordx4 v[16:19], v[0:1], off nt
	s_nop 0
	global_load_dwordx4 v[0:3], v[2:3], off nt
	s_nop 0
	global_load_dwordx4 v[28:31], v[28:29], off nt
	s_nop 0
	global_load_dwordx4 v[32:35], v[44:45], off nt
	global_load_dwordx4 v[36:39], v[44:45], off offset:64 nt
	global_load_dwordx4 v[40:43], v[44:45], off offset:128 nt
	s_nop 0
	global_load_dwordx4 v[44:47], v[44:45], off offset:192 nt
